# in-proj and out GEMM epilogues: the lane^16 / lane^32 row-sum shuffles use v_permlane16/32_swap instead of ds_bpermute (no LDS round trip per hop)
# speedup vs baseline: 1.0161x; 1.0161x over previous
.LBB0_259:
	s_lshl_b32 s15, s22, 8
	v_or_b32_e32 v160, s15, v155
	s_lshl_b32 s13, s24, 8
	v_ashrrev_i32_e32 v161, 31, v160
	v_add_u32_e32 v142, s13, v146
	v_lshl_add_u64 v[164:165], v[160:161], 1, s[10:11]
	v_mad_i64_i32 v[166:167], s[24:25], v142, s69, v[164:165]
	v_cvt_pk_bf16_f32 v160, v124, v125
	v_cvt_pk_bf16_f32 v161, v126, v127
	v_cvt_pk_bf16_f32 v162, v120, v121
	v_cvt_pk_bf16_f32 v163, v122, v123
	global_store_dwordx4 v[166:167], v[160:163], off
	v_or_b32_e32 v143, 16, v142
	s_cmp_gt_i32 s22, 2
	v_cvt_pk_bf16_f32 v160, v68, v69
	v_cvt_pk_bf16_f32 v161, v70, v71
	v_cvt_pk_bf16_f32 v162, v60, v61
	v_cvt_pk_bf16_f32 v163, v62, v63
	global_store_dwordx4 v[166:167], v[160:163], off offset:256
	v_mad_i64_i32 v[166:167], s[24:25], v143, s69, v[164:165]
	s_nop 0
	v_cvt_pk_bf16_f32 v160, v116, v117
	v_cvt_pk_bf16_f32 v161, v118, v119
	v_cvt_pk_bf16_f32 v162, v112, v113
	v_cvt_pk_bf16_f32 v163, v114, v115
	global_store_dwordx4 v[166:167], v[160:163], off
	v_or_b32_e32 v143, 32, v142
	s_nop 0
	v_cvt_pk_bf16_f32 v160, v52, v53
	v_cvt_pk_bf16_f32 v161, v54, v55
	v_cvt_pk_bf16_f32 v162, v48, v49
	v_cvt_pk_bf16_f32 v163, v50, v51
	global_store_dwordx4 v[166:167], v[160:163], off offset:256
	v_mad_i64_i32 v[166:167], s[24:25], v143, s69, v[164:165]
	s_nop 0
	v_cvt_pk_bf16_f32 v160, v108, v109
	v_cvt_pk_bf16_f32 v161, v110, v111
	v_cvt_pk_bf16_f32 v162, v104, v105
	v_cvt_pk_bf16_f32 v163, v106, v107
	global_store_dwordx4 v[166:167], v[160:163], off
	v_or_b32_e32 v143, 48, v142
	s_nop 0
	v_cvt_pk_bf16_f32 v160, v44, v45
	v_cvt_pk_bf16_f32 v161, v46, v47
	v_cvt_pk_bf16_f32 v162, v40, v41
	v_cvt_pk_bf16_f32 v163, v42, v43
	global_store_dwordx4 v[166:167], v[160:163], off offset:256
	v_mad_i64_i32 v[166:167], s[24:25], v143, s69, v[164:165]
	s_nop 0
	v_cvt_pk_bf16_f32 v160, v100, v101
	v_cvt_pk_bf16_f32 v161, v102, v103
	v_cvt_pk_bf16_f32 v162, v96, v97
	v_cvt_pk_bf16_f32 v163, v98, v99
	global_store_dwordx4 v[166:167], v[160:163], off
	v_add_u32_e32 v143, 0x80, v142
	s_nop 0
	v_cvt_pk_bf16_f32 v160, v36, v37
	v_cvt_pk_bf16_f32 v161, v38, v39
	v_cvt_pk_bf16_f32 v162, v32, v33
	v_cvt_pk_bf16_f32 v163, v34, v35
	global_store_dwordx4 v[166:167], v[160:163], off offset:256
	v_mad_i64_i32 v[166:167], s[24:25], v143, s69, v[164:165]
	s_nop 0
	v_cvt_pk_bf16_f32 v160, v92, v93
	v_cvt_pk_bf16_f32 v161, v94, v95
	v_cvt_pk_bf16_f32 v162, v88, v89
	v_cvt_pk_bf16_f32 v163, v90, v91
	global_store_dwordx4 v[166:167], v[160:163], off
	v_add_u32_e32 v143, 0x90, v142
	s_nop 0
	v_cvt_pk_bf16_f32 v160, v28, v29
	v_cvt_pk_bf16_f32 v161, v30, v31
	v_cvt_pk_bf16_f32 v162, v24, v25
	v_cvt_pk_bf16_f32 v163, v26, v27
	global_store_dwordx4 v[166:167], v[160:163], off offset:256
	v_mad_i64_i32 v[166:167], s[24:25], v143, s69, v[164:165]
	s_nop 0
	v_cvt_pk_bf16_f32 v160, v84, v85
	v_cvt_pk_bf16_f32 v161, v86, v87
	v_cvt_pk_bf16_f32 v162, v80, v81
	v_cvt_pk_bf16_f32 v163, v82, v83
	global_store_dwordx4 v[166:167], v[160:163], off
	v_add_u32_e32 v143, 0xa0, v142
	s_nop 0
	v_cvt_pk_bf16_f32 v160, v20, v21
	v_cvt_pk_bf16_f32 v161, v22, v23
	v_cvt_pk_bf16_f32 v162, v16, v17
	v_cvt_pk_bf16_f32 v163, v18, v19
	global_store_dwordx4 v[166:167], v[160:163], off offset:256
	v_mad_i64_i32 v[166:167], s[24:25], v143, s69, v[164:165]
	s_nop 0
	v_cvt_pk_bf16_f32 v160, v76, v77
	v_cvt_pk_bf16_f32 v161, v78, v79
	v_cvt_pk_bf16_f32 v162, v72, v73
	v_cvt_pk_bf16_f32 v163, v74, v75
	global_store_dwordx4 v[166:167], v[160:163], off
	v_add_u32_e32 v143, 0xb0, v142
	v_mad_i64_i32 v[164:165], s[24:25], v143, s69, v[164:165]
	v_cvt_pk_bf16_f32 v160, v12, v13
	v_cvt_pk_bf16_f32 v161, v14, v15
	v_cvt_pk_bf16_f32 v162, v8, v9
	v_cvt_pk_bf16_f32 v163, v10, v11
	global_store_dwordx4 v[166:167], v[160:163], off offset:256
	s_nop 1
	v_cvt_pk_bf16_f32 v160, v64, v65
	v_cvt_pk_bf16_f32 v161, v66, v67
	v_cvt_pk_bf16_f32 v162, v56, v57
	v_cvt_pk_bf16_f32 v163, v58, v59
	global_store_dwordx4 v[164:165], v[160:163], off
	s_nop 1
	v_cvt_pk_bf16_f32 v160, v4, v5
	v_cvt_pk_bf16_f32 v161, v6, v7
	v_cvt_pk_bf16_f32 v162, v0, v1
	v_cvt_pk_bf16_f32 v163, v2, v3
	global_store_dwordx4 v[164:165], v[160:163], off offset:256
	s_cbranch_scc1 .LBB0_294
	v_mul_f32_e32 v125, v125, v125
	v_fmac_f32_e32 v125, v124, v124
	v_mul_f32_e32 v124, v127, v127
	v_and_b32_e32 v160, 64, v159
	v_fmac_f32_e32 v124, v126, v126
	v_mul_f32_e32 v121, v121, v121
	v_xor_b32_e32 v143, 16, v159
	v_add_u32_e32 v161, 64, v160
	v_add_f32_e32 v124, v125, v124
	v_fmac_f32_e32 v121, v120, v120
	v_cmp_lt_i32_e32 vcc, v143, v161
	v_add_f32_e32 v120, v124, v121
	v_mul_f32_e32 v121, v123, v123
	v_cndmask_b32_e32 v143, v159, v143, vcc
	v_fmac_f32_e32 v121, v122, v122
	v_lshlrev_b32_e32 v160, 2, v143
	v_add_f32_e32 v121, v121, v120
	v_mov_b32_e32 v122, v121
	s_nop 1
	v_permlane16_swap_b32_e32 v122, v121
	v_xor_b32_e32 v120, 32, v159
	v_cmp_lt_i32_e32 vcc, v120, v161
	s_cmp_eq_u32 s22, 2
	v_ashrrev_i32_e32 v143, 31, v142
	v_cndmask_b32_e32 v120, v159, v120, vcc
	v_lshlrev_b32_e32 v120, 2, v120
	s_waitcnt lgkmcnt(0)
	v_add_f32_e32 v121, v121, v122
	v_mov_b32_e32 v122, v121
	s_nop 1
	v_permlane32_swap_b32_e32 v122, v121
	s_cselect_b32 s23, s50, s55
	s_cselect_b32 s22, s49, s54
	s_and_saveexec_b64 s[24:25], s[2:3]
	s_cbranch_execz .LBB0_262
	v_lshl_add_u64 v[124:125], v[142:143], 2, s[22:23]
	s_waitcnt lgkmcnt(0)
	v_add_f32_e32 v121, v121, v122
	global_atomic_add_f32 v[124:125], v121, off
.LBB0_262:
	s_or_b64 exec, exec, s[24:25]
	v_mul_f32_e32 v117, v117, v117
	v_fmac_f32_e32 v117, v116, v116
	v_mul_f32_e32 v116, v119, v119
	v_fmac_f32_e32 v116, v118, v118
	v_mul_f32_e32 v113, v113, v113
	v_add_f32_e32 v116, v117, v116
	v_fmac_f32_e32 v113, v112, v112
	v_add_f32_e32 v112, v116, v113
	v_mul_f32_e32 v113, v115, v115
	v_fmac_f32_e32 v113, v114, v114
	v_add_f32_e32 v112, v113, v112
	v_mov_b32_e32 v113, v112
	s_nop 1
	v_permlane16_swap_b32_e32 v113, v112
	s_waitcnt lgkmcnt(0)
	v_add_f32_e32 v112, v112, v113
	v_mov_b32_e32 v113, v112
	s_nop 1
	v_permlane32_swap_b32_e32 v113, v112
	s_and_saveexec_b64 s[24:25], s[2:3]
	s_cbranch_execz .LBB0_264
	v_add_u32_e32 v114, s13, v148
	v_ashrrev_i32_e32 v115, 31, v114
	v_lshl_add_u64 v[114:115], v[114:115], 2, s[22:23]
	s_waitcnt lgkmcnt(0)
	v_add_f32_e32 v112, v112, v113
	global_atomic_add_f32 v[114:115], v112, off
.LBB0_264:
	s_or_b64 exec, exec, s[24:25]
	v_mul_f32_e32 v109, v109, v109
	v_fmac_f32_e32 v109, v108, v108
	v_mul_f32_e32 v108, v111, v111
	v_fmac_f32_e32 v108, v110, v110
	v_mul_f32_e32 v105, v105, v105
	v_add_f32_e32 v108, v109, v108
	v_fmac_f32_e32 v105, v104, v104
	v_add_f32_e32 v104, v108, v105
	v_mul_f32_e32 v105, v107, v107
	v_fmac_f32_e32 v105, v106, v106
	v_add_f32_e32 v104, v105, v104
	v_mov_b32_e32 v105, v104
	s_nop 1
	v_permlane16_swap_b32_e32 v105, v104
	s_waitcnt lgkmcnt(0)
	v_add_f32_e32 v104, v104, v105
	v_mov_b32_e32 v105, v104
	s_nop 1
	v_permlane32_swap_b32_e32 v105, v104
	s_and_saveexec_b64 s[24:25], s[2:3]
	s_cbranch_execz .LBB0_266
	v_add_u32_e32 v106, s13, v149
	v_ashrrev_i32_e32 v107, 31, v106
	v_lshl_add_u64 v[106:107], v[106:107], 2, s[22:23]
	s_waitcnt lgkmcnt(0)
	v_add_f32_e32 v104, v104, v105
	global_atomic_add_f32 v[106:107], v104, off
.LBB0_266:
	s_or_b64 exec, exec, s[24:25]
	v_mul_f32_e32 v101, v101, v101
	v_fmac_f32_e32 v101, v100, v100
	v_mul_f32_e32 v100, v103, v103
	v_fmac_f32_e32 v100, v102, v102
	v_mul_f32_e32 v97, v97, v97
	v_add_f32_e32 v100, v101, v100
	v_fmac_f32_e32 v97, v96, v96
	v_add_f32_e32 v96, v100, v97
	v_mul_f32_e32 v97, v99, v99
	v_fmac_f32_e32 v97, v98, v98
	v_add_f32_e32 v96, v97, v96
	v_mov_b32_e32 v97, v96
	s_nop 1
	v_permlane16_swap_b32_e32 v97, v96
	s_waitcnt lgkmcnt(0)
	v_add_f32_e32 v96, v96, v97
	v_mov_b32_e32 v97, v96
	s_nop 1
	v_permlane32_swap_b32_e32 v97, v96
	s_and_saveexec_b64 s[24:25], s[2:3]
	s_cbranch_execz .LBB0_268
	v_add_u32_e32 v98, s13, v150
	v_ashrrev_i32_e32 v99, 31, v98
	v_lshl_add_u64 v[98:99], v[98:99], 2, s[22:23]
	s_waitcnt lgkmcnt(0)
	v_add_f32_e32 v96, v96, v97
	global_atomic_add_f32 v[98:99], v96, off
.LBB0_268:
	s_or_b64 exec, exec, s[24:25]
	v_mul_f32_e32 v93, v93, v93
	v_fmac_f32_e32 v93, v92, v92
	v_mul_f32_e32 v92, v95, v95
	v_fmac_f32_e32 v92, v94, v94
	v_mul_f32_e32 v89, v89, v89
	v_add_f32_e32 v92, v93, v92
	v_fmac_f32_e32 v89, v88, v88
	v_add_f32_e32 v88, v92, v89
	v_mul_f32_e32 v89, v91, v91
	v_fmac_f32_e32 v89, v90, v90
	v_add_f32_e32 v88, v89, v88
	v_mov_b32_e32 v89, v88
	s_nop 1
	v_permlane16_swap_b32_e32 v89, v88
	s_waitcnt lgkmcnt(0)
	v_add_f32_e32 v88, v88, v89
	v_mov_b32_e32 v89, v88
	s_nop 1
	v_permlane32_swap_b32_e32 v89, v88
	s_and_saveexec_b64 s[24:25], s[2:3]
	s_cbranch_execz .LBB0_270
	v_add_u32_e32 v90, s13, v151
	v_ashrrev_i32_e32 v91, 31, v90
	v_lshl_add_u64 v[90:91], v[90:91], 2, s[22:23]
	s_waitcnt lgkmcnt(0)
	v_add_f32_e32 v88, v88, v89
	global_atomic_add_f32 v[90:91], v88, off
.LBB0_270:
	s_or_b64 exec, exec, s[24:25]
	v_mul_f32_e32 v85, v85, v85
	v_fmac_f32_e32 v85, v84, v84
	v_mul_f32_e32 v84, v87, v87
	v_fmac_f32_e32 v84, v86, v86
	v_mul_f32_e32 v81, v81, v81
	v_add_f32_e32 v84, v85, v84
	v_fmac_f32_e32 v81, v80, v80
	v_add_f32_e32 v80, v84, v81
	v_mul_f32_e32 v81, v83, v83
	v_fmac_f32_e32 v81, v82, v82
	v_add_f32_e32 v80, v81, v80
	v_mov_b32_e32 v81, v80
	s_nop 1
	v_permlane16_swap_b32_e32 v81, v80
	s_waitcnt lgkmcnt(0)
	v_add_f32_e32 v80, v80, v81
	v_mov_b32_e32 v81, v80
	s_nop 1
	v_permlane32_swap_b32_e32 v81, v80
	s_and_saveexec_b64 s[24:25], s[2:3]
	s_cbranch_execz .LBB0_272
	v_add_u32_e32 v82, s13, v152
	v_ashrrev_i32_e32 v83, 31, v82
	v_lshl_add_u64 v[82:83], v[82:83], 2, s[22:23]
	s_waitcnt lgkmcnt(0)
	v_add_f32_e32 v80, v80, v81
	global_atomic_add_f32 v[82:83], v80, off
.LBB0_272:
	s_or_b64 exec, exec, s[24:25]
	v_mul_f32_e32 v77, v77, v77
	v_fmac_f32_e32 v77, v76, v76
	v_mul_f32_e32 v76, v79, v79
	v_fmac_f32_e32 v76, v78, v78
	v_mul_f32_e32 v73, v73, v73
	v_add_f32_e32 v76, v77, v76
	v_fmac_f32_e32 v73, v72, v72
	v_add_f32_e32 v72, v76, v73
	v_mul_f32_e32 v73, v75, v75
	v_fmac_f32_e32 v73, v74, v74
	v_add_f32_e32 v72, v73, v72
	v_mov_b32_e32 v73, v72
	s_nop 1
	v_permlane16_swap_b32_e32 v73, v72
	s_waitcnt lgkmcnt(0)
	v_add_f32_e32 v72, v72, v73
	v_mov_b32_e32 v73, v72
	s_nop 1
	v_permlane32_swap_b32_e32 v73, v72
	s_and_saveexec_b64 s[24:25], s[2:3]
	s_cbranch_execz .LBB0_274
	v_add_u32_e32 v74, s13, v153
	v_ashrrev_i32_e32 v75, 31, v74
	v_lshl_add_u64 v[74:75], v[74:75], 2, s[22:23]
	s_waitcnt lgkmcnt(0)
	v_add_f32_e32 v72, v72, v73
	global_atomic_add_f32 v[74:75], v72, off
.LBB0_274:
	s_or_b64 exec, exec, s[24:25]
	v_mul_f32_e32 v65, v65, v65
	v_fmac_f32_e32 v65, v64, v64
	v_mul_f32_e32 v64, v67, v67
	v_fmac_f32_e32 v64, v66, v66
	v_mul_f32_e32 v57, v57, v57
	v_add_f32_e32 v64, v65, v64
	v_fmac_f32_e32 v57, v56, v56
	v_add_f32_e32 v56, v64, v57
	v_mul_f32_e32 v57, v59, v59
	v_fmac_f32_e32 v57, v58, v58
	v_add_f32_e32 v56, v57, v56
	v_mov_b32_e32 v57, v56
	s_nop 1
	v_permlane16_swap_b32_e32 v57, v56
	s_waitcnt lgkmcnt(0)
	v_add_f32_e32 v56, v56, v57
	v_mov_b32_e32 v57, v56
	s_nop 1
	v_permlane32_swap_b32_e32 v57, v56
	s_and_saveexec_b64 s[24:25], s[2:3]
	s_cbranch_execz .LBB0_276
	v_add_u32_e32 v58, s13, v154
	v_ashrrev_i32_e32 v59, 31, v58
	v_lshl_add_u64 v[58:59], v[58:59], 2, s[22:23]
	s_waitcnt lgkmcnt(0)
	v_add_f32_e32 v56, v56, v57
	global_atomic_add_f32 v[58:59], v56, off
.LBB0_276:
	s_or_b64 exec, exec, s[24:25]
	s_bitset1_b32 s15, 7
	s_cmpk_lt_i32 s15, 0x280
	s_cselect_b32 s22, s49, 0
	s_cselect_b32 s23, s50, 0
	s_cmpk_lt_i32 s15, 0x180
	s_cselect_b32 s23, s55, s23
	s_cselect_b32 s22, s54, s22
	s_cmp_eq_u64 s[22:23], 0
	s_cbranch_scc1 .LBB0_294
	v_mul_f32_e32 v56, v69, v69
	s_waitcnt lgkmcnt(0)
	v_mul_f32_e32 v57, v71, v71
	v_fmac_f32_e32 v56, v68, v68
	v_fmac_f32_e32 v57, v70, v70
	v_add_f32_e32 v56, v56, v57
	v_mul_f32_e32 v57, v61, v61
	v_fmac_f32_e32 v57, v60, v60
	v_add_f32_e32 v56, v56, v57
	v_mul_f32_e32 v57, v63, v63
	v_fmac_f32_e32 v57, v62, v62
	v_add_f32_e32 v56, v57, v56
	v_mov_b32_e32 v57, v56
	s_nop 1
	v_permlane16_swap_b32_e32 v57, v56
	s_waitcnt lgkmcnt(0)
	v_add_f32_e32 v56, v56, v57
	v_mov_b32_e32 v57, v56
	s_nop 1
	v_permlane32_swap_b32_e32 v57, v56
	s_and_saveexec_b64 s[24:25], s[2:3]
	s_cbranch_execz .LBB0_279
	v_lshl_add_u64 v[58:59], v[142:143], 2, s[22:23]
	s_waitcnt lgkmcnt(0)
	v_add_f32_e32 v56, v56, v57
	global_atomic_add_f32 v[58:59], v56, off
.LBB0_279:
	s_or_b64 exec, exec, s[24:25]
	v_mul_f32_e32 v53, v53, v53
	v_fmac_f32_e32 v53, v52, v52
	v_mul_f32_e32 v52, v55, v55
	v_fmac_f32_e32 v52, v54, v54
	v_mul_f32_e32 v49, v49, v49
	v_add_f32_e32 v52, v53, v52
	v_fmac_f32_e32 v49, v48, v48
	v_add_f32_e32 v48, v52, v49
	v_mul_f32_e32 v49, v51, v51
	v_fmac_f32_e32 v49, v50, v50
	v_add_f32_e32 v48, v49, v48
	v_mov_b32_e32 v49, v48
	s_nop 1
	v_permlane16_swap_b32_e32 v49, v48
	s_waitcnt lgkmcnt(0)
	v_add_f32_e32 v48, v48, v49
	v_mov_b32_e32 v49, v48
	s_nop 1
	v_permlane32_swap_b32_e32 v49, v48
	s_and_saveexec_b64 s[24:25], s[2:3]
	s_cbranch_execz .LBB0_281
	v_add_u32_e32 v50, s13, v148
	v_ashrrev_i32_e32 v51, 31, v50
	v_lshl_add_u64 v[50:51], v[50:51], 2, s[22:23]
	s_waitcnt lgkmcnt(0)
	v_add_f32_e32 v48, v48, v49
	global_atomic_add_f32 v[50:51], v48, off
.LBB0_281:
	s_or_b64 exec, exec, s[24:25]
	v_mul_f32_e32 v45, v45, v45
	v_fmac_f32_e32 v45, v44, v44
	v_mul_f32_e32 v44, v47, v47
	v_fmac_f32_e32 v44, v46, v46
	v_mul_f32_e32 v41, v41, v41
	v_add_f32_e32 v44, v45, v44
	v_fmac_f32_e32 v41, v40, v40
	v_add_f32_e32 v40, v44, v41
	v_mul_f32_e32 v41, v43, v43
	v_fmac_f32_e32 v41, v42, v42
	v_add_f32_e32 v40, v41, v40
	v_mov_b32_e32 v41, v40
	s_nop 1
	v_permlane16_swap_b32_e32 v41, v40
	s_waitcnt lgkmcnt(0)
	v_add_f32_e32 v40, v40, v41
	v_mov_b32_e32 v41, v40
	s_nop 1
	v_permlane32_swap_b32_e32 v41, v40
	s_and_saveexec_b64 s[24:25], s[2:3]
	s_cbranch_execz .LBB0_283
	v_add_u32_e32 v42, s13, v149
	v_ashrrev_i32_e32 v43, 31, v42
	v_lshl_add_u64 v[42:43], v[42:43], 2, s[22:23]
	s_waitcnt lgkmcnt(0)
	v_add_f32_e32 v40, v40, v41
	global_atomic_add_f32 v[42:43], v40, off
.LBB0_283:
	s_or_b64 exec, exec, s[24:25]
	v_mul_f32_e32 v37, v37, v37
	v_fmac_f32_e32 v37, v36, v36
	v_mul_f32_e32 v36, v39, v39
	v_fmac_f32_e32 v36, v38, v38
	v_mul_f32_e32 v33, v33, v33
	v_add_f32_e32 v36, v37, v36
	v_fmac_f32_e32 v33, v32, v32
	v_add_f32_e32 v32, v36, v33
	v_mul_f32_e32 v33, v35, v35
	v_fmac_f32_e32 v33, v34, v34
	v_add_f32_e32 v32, v33, v32
	v_mov_b32_e32 v33, v32
	s_nop 1
	v_permlane16_swap_b32_e32 v33, v32
	s_waitcnt lgkmcnt(0)
	v_add_f32_e32 v32, v32, v33
	v_mov_b32_e32 v33, v32
	s_nop 1
	v_permlane32_swap_b32_e32 v33, v32
	s_and_saveexec_b64 s[24:25], s[2:3]
	s_cbranch_execz .LBB0_285
	v_add_u32_e32 v34, s13, v150
	v_ashrrev_i32_e32 v35, 31, v34
	v_lshl_add_u64 v[34:35], v[34:35], 2, s[22:23]
	s_waitcnt lgkmcnt(0)
	v_add_f32_e32 v32, v32, v33
	global_atomic_add_f32 v[34:35], v32, off
.LBB0_285:
	s_or_b64 exec, exec, s[24:25]
	v_mul_f32_e32 v29, v29, v29
	v_fmac_f32_e32 v29, v28, v28
	v_mul_f32_e32 v28, v31, v31
	v_fmac_f32_e32 v28, v30, v30
	v_mul_f32_e32 v25, v25, v25
	v_add_f32_e32 v28, v29, v28
	v_fmac_f32_e32 v25, v24, v24
	v_add_f32_e32 v24, v28, v25
	v_mul_f32_e32 v25, v27, v27
	v_fmac_f32_e32 v25, v26, v26
	v_add_f32_e32 v24, v25, v24
	v_mov_b32_e32 v25, v24
	s_nop 1
	v_permlane16_swap_b32_e32 v25, v24
	s_waitcnt lgkmcnt(0)
	v_add_f32_e32 v24, v24, v25
	v_mov_b32_e32 v25, v24
	s_nop 1
	v_permlane32_swap_b32_e32 v25, v24
	s_and_saveexec_b64 s[24:25], s[2:3]
	s_cbranch_execz .LBB0_287
	v_add_u32_e32 v26, s13, v151
	v_ashrrev_i32_e32 v27, 31, v26
	v_lshl_add_u64 v[26:27], v[26:27], 2, s[22:23]
	s_waitcnt lgkmcnt(0)
	v_add_f32_e32 v24, v24, v25
	global_atomic_add_f32 v[26:27], v24, off
.LBB0_287:
	s_or_b64 exec, exec, s[24:25]
	v_mul_f32_e32 v21, v21, v21
	v_fmac_f32_e32 v21, v20, v20
	v_mul_f32_e32 v20, v23, v23
	v_fmac_f32_e32 v20, v22, v22
	v_mul_f32_e32 v17, v17, v17
	v_add_f32_e32 v20, v21, v20
	v_fmac_f32_e32 v17, v16, v16
	v_add_f32_e32 v16, v20, v17
	v_mul_f32_e32 v17, v19, v19
	v_fmac_f32_e32 v17, v18, v18
	v_add_f32_e32 v16, v17, v16
	v_mov_b32_e32 v17, v16
	s_nop 1
	v_permlane16_swap_b32_e32 v17, v16
	s_waitcnt lgkmcnt(0)
	v_add_f32_e32 v16, v16, v17
	v_mov_b32_e32 v17, v16
	s_nop 1
	v_permlane32_swap_b32_e32 v17, v16
	s_and_saveexec_b64 s[24:25], s[2:3]
	s_cbranch_execz .LBB0_289
	v_add_u32_e32 v18, s13, v152
	v_ashrrev_i32_e32 v19, 31, v18
	v_lshl_add_u64 v[18:19], v[18:19], 2, s[22:23]
	s_waitcnt lgkmcnt(0)
	v_add_f32_e32 v16, v16, v17
	global_atomic_add_f32 v[18:19], v16, off
.LBB0_289:
	s_or_b64 exec, exec, s[24:25]
	v_mul_f32_e32 v13, v13, v13
	v_fmac_f32_e32 v13, v12, v12
	v_mul_f32_e32 v12, v15, v15
	v_fmac_f32_e32 v12, v14, v14
	v_mul_f32_e32 v9, v9, v9
	v_add_f32_e32 v12, v13, v12
	v_fmac_f32_e32 v9, v8, v8
	v_add_f32_e32 v8, v12, v9
	v_mul_f32_e32 v9, v11, v11
	v_fmac_f32_e32 v9, v10, v10
	v_add_f32_e32 v8, v9, v8
	v_mov_b32_e32 v9, v8
	s_nop 1
	v_permlane16_swap_b32_e32 v9, v8
	s_waitcnt lgkmcnt(0)
	v_add_f32_e32 v8, v8, v9
	v_mov_b32_e32 v9, v8
	s_nop 1
	v_permlane32_swap_b32_e32 v9, v8
	s_and_saveexec_b64 s[24:25], s[2:3]
	s_cbranch_execz .LBB0_291
	v_add_u32_e32 v10, s13, v153
	v_ashrrev_i32_e32 v11, 31, v10
	v_lshl_add_u64 v[10:11], v[10:11], 2, s[22:23]
	s_waitcnt lgkmcnt(0)
	v_add_f32_e32 v8, v8, v9
	global_atomic_add_f32 v[10:11], v8, off
.LBB0_291:
	s_or_b64 exec, exec, s[24:25]
	v_mul_f32_e32 v5, v5, v5
	v_fmac_f32_e32 v5, v4, v4
	v_mul_f32_e32 v4, v7, v7
	v_fmac_f32_e32 v4, v6, v6
	v_mul_f32_e32 v1, v1, v1
	v_add_f32_e32 v4, v5, v4
	v_fmac_f32_e32 v1, v0, v0
	v_add_f32_e32 v0, v4, v1
	v_mul_f32_e32 v1, v3, v3
	v_fmac_f32_e32 v1, v2, v2
	v_add_f32_e32 v0, v1, v0
	v_mov_b32_e32 v1, v0
	s_nop 1
	v_permlane16_swap_b32_e32 v1, v0
	s_waitcnt lgkmcnt(0)
	v_add_f32_e32 v0, v0, v1
	v_mov_b32_e32 v1, v0
	s_nop 1
	v_permlane32_swap_b32_e32 v1, v0
	s_and_saveexec_b64 s[24:25], s[2:3]
	s_cbranch_execz .LBB0_293
	v_add_u32_e32 v2, s13, v154
	v_ashrrev_i32_e32 v3, 31, v2
	v_lshl_add_u64 v[2:3], v[2:3], 2, s[22:23]
	s_waitcnt lgkmcnt(0)
	v_add_f32_e32 v0, v0, v1
	global_atomic_add_f32 v[2:3], v0, off

.LBB0_1012:
	s_ashr_i32 s17, s24, 4
	s_mul_hi_i32 s19, s17, 0x6000
	s_mulk_i32 s17, 0x6000
	s_add_u32 s17, s96, s17
	s_addc_u32 s19, s97, s19
	v_lshl_or_b32 v162, s26, 8, v181
	s_add_u32 s26, s17, 0x2000
	s_addc_u32 s27, s19, 0
	s_add_u32 s28, s17, 0x4000
	s_addc_u32 s29, s19, 0
	v_ashrrev_i32_e32 v163, 31, v162
	s_lshl_b32 s17, s24, 8
	v_lshlrev_b64 v[80:81], 2, v[162:163]
	v_add_u32_e32 v166, s17, v176
	v_lshl_add_u64 v[92:93], s[76:77], 0, v[80:81]
	v_lshl_add_u64 v[84:85], s[28:29], 0, v[80:81]
	v_ashrrev_i32_e32 v167, 31, v166
	global_load_dwordx4 v[188:191], v[92:93], off offset:16
	global_load_dwordx4 v[168:171], v[92:93], off
	global_load_dwordx4 v[172:175], v[84:85], off offset:16
	global_load_dwordx4 v[192:195], v[84:85], off
	v_lshlrev_b64 v[84:85], 12, v[166:167]
	v_lshl_add_u64 v[84:85], s[64:65], 0, v[84:85]
	v_lshl_add_u64 v[220:221], v[84:85], 0, v[80:81]
	v_lshl_add_u64 v[82:83], s[26:27], 0, v[80:81]
	global_load_dwordx4 v[196:199], v[220:221], off
	global_load_dwordx4 v[88:91], v[82:83], off
	global_load_dwordx4 v[84:87], v[82:83], off offset:16
	global_load_dwordx4 v[200:203], v[220:221], off offset:16
	v_or_b32_e32 v80, 0x80, v162
	v_or_b32_e32 v82, 0x84, v162
	v_ashrrev_i32_e32 v81, 31, v80
	v_lshlrev_b64 v[222:223], 11, v[166:167]
	v_ashrrev_i32_e32 v83, 31, v82
	v_lshlrev_b64 v[164:165], 1, v[162:163]
	v_lshlrev_b64 v[80:81], 2, v[80:81]
	v_lshl_add_u64 v[224:225], s[52:53], 0, v[222:223]
	global_load_dwordx4 v[204:207], v[92:93], off offset:528
	global_load_dwordx4 v[208:211], v[92:93], off offset:512
	v_lshl_add_u64 v[92:93], s[26:27], 0, v[80:81]
	v_lshl_add_u64 v[82:83], v[82:83], 2, s[26:27]
	v_lshl_add_u64 v[80:81], s[28:29], 0, v[80:81]
	v_lshl_add_u64 v[222:223], s[12:13], 0, v[222:223]
	v_lshl_add_u64 v[224:225], v[224:225], 0, v[164:165]
	global_load_dwordx4 v[92:95], v[92:93], off
	s_nop 0
	global_load_dwordx4 v[212:215], v[80:81], off
	global_load_dwordx4 v[216:219], v[80:81], off offset:16
	s_nop 0
	global_load_dwordx4 v[80:83], v[82:83], off
	v_lshl_add_u64 v[222:223], v[222:223], 0, v[164:165]
	s_waitcnt vmcnt(0)
	v_pk_add_f32 v[226:227], v[174:175], 1.0 op_sel_hi:[1,0]
	v_pk_add_f32 v[194:195], v[194:195], 1.0 op_sel_hi:[1,0]
	v_pk_add_f32 v[192:193], v[192:193], 1.0 op_sel_hi:[1,0]
	v_pk_add_f32 v[172:173], v[172:173], 1.0 op_sel_hi:[1,0]
	v_pk_mul_f32 v[170:171], v[170:171], v[194:195]
	v_pk_mul_f32 v[174:175], v[168:169], v[192:193]
	v_pk_mul_f32 v[168:169], v[190:191], v[226:227]
	v_pk_mul_f32 v[172:173], v[188:189], v[172:173]
	v_pk_fma_f32 v[198:199], v[142:143], v[90:91], v[198:199]
	v_pk_fma_f32 v[226:227], v[140:141], v[88:89], v[196:197]
	v_pk_fma_f32 v[202:203], v[138:139], v[86:87], v[202:203]
	v_pk_fma_f32 v[200:201], v[136:137], v[84:85], v[200:201]
	v_cvt_pk_bf16_f32 v136, v226, v227
	v_cvt_pk_bf16_f32 v137, v198, v199
	v_cvt_pk_bf16_f32 v138, v200, v201
	v_cvt_pk_bf16_f32 v139, v202, v203
	v_pk_mul_f32 v[140:141], v[170:171], v[198:199]
	v_pk_mul_f32 v[142:143], v[174:175], v[226:227]
	v_pk_mul_f32 v[188:189], v[168:169], v[202:203]
	v_pk_mul_f32 v[190:191], v[172:173], v[200:201]
	global_store_dwordx4 v[224:225], v[136:139], off
	v_mul_f32_e32 v199, v199, v199
	v_mul_f32_e32 v201, v201, v201
	v_cvt_pk_bf16_f32 v136, v142, v143
	v_cvt_pk_bf16_f32 v137, v140, v141
	v_cvt_pk_bf16_f32 v138, v190, v191
	v_cvt_pk_bf16_f32 v139, v188, v189
	global_store_dwordx4 v[222:223], v[136:139], off
	global_load_dwordx4 v[190:193], v[220:221], off offset:512
	global_load_dwordx4 v[194:197], v[220:221], off offset:528
	v_mul_f32_e32 v189, v227, v227
	v_and_b32_e32 v137, 64, v186
	v_fmac_f32_e32 v189, v226, v226
	v_fmac_f32_e32 v199, v198, v198
	v_xor_b32_e32 v136, 16, v186
	v_add_u32_e32 v137, 64, v137
	v_mul_f32_e32 v203, v203, v203
	v_fmac_f32_e32 v201, v200, v200
	v_add_f32_e32 v189, v189, v199
	v_cmp_lt_i32_e32 vcc, v136, v137
	v_fmac_f32_e32 v203, v202, v202
	v_add_f32_e32 v189, v189, v201
	v_cndmask_b32_e32 v136, v186, v136, vcc
	v_add_f32_e32 v189, v203, v189
	v_lshlrev_b32_e32 v188, 2, v136
	v_xor_b32_e32 v138, 32, v186
	v_cmp_lt_i32_e32 vcc, v138, v137
	s_waitcnt vmcnt(1)
	v_pk_fma_f32 v[134:135], v[134:135], v[94:95], v[192:193]
	v_pk_fma_f32 v[132:133], v[132:133], v[92:93], v[190:191]
	s_waitcnt vmcnt(0)
	v_pk_fma_f32 v[190:191], v[130:131], v[82:83], v[196:197]
	v_pk_fma_f32 v[192:193], v[128:129], v[80:81], v[194:195]
	v_mul_f32_e32 v194, v133, v133
	v_mul_f32_e32 v195, v135, v135
	v_cvt_pk_bf16_f32 v128, v132, v133
	v_cvt_pk_bf16_f32 v129, v134, v135
	v_cvt_pk_bf16_f32 v130, v192, v193
	v_cvt_pk_bf16_f32 v131, v190, v191
	v_mul_f32_e32 v196, v193, v193
	v_fmac_f32_e32 v194, v132, v132
	v_fmac_f32_e32 v195, v134, v134
	v_mul_f32_e32 v197, v191, v191
	global_store_dwordx4 v[224:225], v[128:131], off offset:256
	v_fmac_f32_e32 v196, v192, v192
	v_fmac_f32_e32 v197, v190, v190
	v_add_f32_e32 v128, v194, v195
	v_add_f32_e32 v128, v128, v196
	v_add_f32_e32 v128, v197, v128
	v_add_f32_e32 v131, v189, v128
	v_mov_b32_e32 v189, v131
	s_nop 1
	v_permlane16_swap_b32_e32 v189, v131
	v_cndmask_b32_e32 v137, v186, v138, vcc
	v_pk_add_f32 v[138:139], v[212:213], 1.0 op_sel_hi:[1,0]
	v_lshlrev_b32_e32 v187, 2, v137
	v_pk_mul_f32 v[140:141], v[208:209], v[138:139]
	v_pk_add_f32 v[136:137], v[214:215], 1.0 op_sel_hi:[1,0]
	v_pk_mul_f32 v[128:129], v[140:141], v[132:133]
	v_pk_add_f32 v[212:213], v[218:219], 1.0 op_sel_hi:[1,0]
	v_cvt_pk_bf16_f32 v130, v128, v129
	s_waitcnt lgkmcnt(0)
	v_add_f32_e32 v128, v131, v189
	v_mov_b32_e32 v129, v128
	s_nop 1
	v_permlane32_swap_b32_e32 v129, v128
	v_pk_add_f32 v[214:215], v[216:217], 1.0 op_sel_hi:[1,0]
	v_pk_mul_f32 v[142:143], v[210:211], v[136:137]
	v_pk_mul_f32 v[136:137], v[206:207], v[212:213]
	v_pk_mul_f32 v[138:139], v[204:205], v[214:215]
	v_pk_mul_f32 v[134:135], v[142:143], v[134:135]
	v_pk_mul_f32 v[190:191], v[136:137], v[190:191]
	v_pk_mul_f32 v[132:133], v[138:139], v[192:193]
	v_cvt_pk_bf16_f32 v131, v134, v135
	v_cvt_pk_bf16_f32 v132, v132, v133
	v_cvt_pk_bf16_f32 v133, v190, v191
	global_store_dwordx4 v[222:223], v[130:133], off offset:256
	s_and_saveexec_b64 s[24:25], s[2:3]
	s_cbranch_execz .LBB0_1014
	v_lshl_add_u64 v[130:131], v[166:167], 2, s[14:15]
	s_waitcnt lgkmcnt(0)
	v_add_f32_e32 v128, v128, v129
	global_atomic_add_f32 v[130:131], v128, off
.LBB0_1014:
	s_or_b64 exec, exec, s[24:25]
	v_add_u32_e32 v128, s17, v178
	s_waitcnt lgkmcnt(0)
	v_ashrrev_i32_e32 v129, 31, v128
	v_lshlrev_b64 v[130:131], 12, v[128:129]
	v_lshl_add_u64 v[130:131], s[64:65], 0, v[130:131]
	v_lshl_add_u64 v[134:135], v[162:163], 2, v[130:131]
	global_load_dwordx4 v[130:133], v[134:135], off
	global_load_dwordx4 v[190:193], v[134:135], off offset:16
	v_lshlrev_b64 v[194:195], 11, v[128:129]
	v_lshl_add_u64 v[196:197], s[52:53], 0, v[194:195]
	v_lshl_add_u64 v[194:195], s[12:13], 0, v[194:195]
	v_lshl_add_u64 v[196:197], v[196:197], 0, v[164:165]
	v_lshl_add_u64 v[194:195], v[194:195], 0, v[164:165]
	s_waitcnt vmcnt(1)
	v_pk_fma_f32 v[132:133], v[126:127], v[90:91], v[132:133]
	v_pk_fma_f32 v[130:131], v[124:125], v[88:89], v[130:131]
	s_waitcnt vmcnt(0)
	v_pk_fma_f32 v[192:193], v[122:123], v[86:87], v[192:193]
	v_pk_fma_f32 v[190:191], v[120:121], v[84:85], v[190:191]
	v_cvt_pk_bf16_f32 v120, v130, v131
	v_cvt_pk_bf16_f32 v121, v132, v133
	v_cvt_pk_bf16_f32 v122, v190, v191
	v_cvt_pk_bf16_f32 v123, v192, v193
	v_pk_mul_f32 v[124:125], v[170:171], v[132:133]
	v_pk_mul_f32 v[126:127], v[174:175], v[130:131]
	v_pk_mul_f32 v[198:199], v[168:169], v[192:193]
	v_pk_mul_f32 v[200:201], v[172:173], v[190:191]
	global_store_dwordx4 v[196:197], v[120:123], off
	v_mul_f32_e32 v131, v131, v131
	v_mul_f32_e32 v133, v133, v133
	v_cvt_pk_bf16_f32 v120, v126, v127
	v_cvt_pk_bf16_f32 v121, v124, v125
	v_cvt_pk_bf16_f32 v122, v200, v201
	v_cvt_pk_bf16_f32 v123, v198, v199
	global_store_dwordx4 v[194:195], v[120:123], off
	global_load_dwordx4 v[120:123], v[134:135], off offset:512
	s_nop 0
	global_load_dwordx4 v[124:127], v[134:135], off offset:528
	v_mul_f32_e32 v134, v191, v191
	v_fmac_f32_e32 v131, v130, v130
	v_fmac_f32_e32 v133, v132, v132
	v_mul_f32_e32 v135, v193, v193
	v_fmac_f32_e32 v134, v190, v190
	v_add_f32_e32 v130, v131, v133
	v_fmac_f32_e32 v135, v192, v192
	v_add_f32_e32 v130, v130, v134
	v_add_f32_e32 v130, v135, v130
	s_waitcnt vmcnt(1)
	v_pk_fma_f32 v[118:119], v[118:119], v[94:95], v[122:123]
	v_pk_fma_f32 v[116:117], v[116:117], v[92:93], v[120:121]
	s_waitcnt vmcnt(0)
	v_pk_fma_f32 v[120:121], v[114:115], v[82:83], v[126:127]
	v_pk_fma_f32 v[122:123], v[112:113], v[80:81], v[124:125]
	v_mul_f32_e32 v124, v117, v117
	v_mul_f32_e32 v125, v119, v119
	v_cvt_pk_bf16_f32 v112, v116, v117
	v_cvt_pk_bf16_f32 v113, v118, v119
	v_cvt_pk_bf16_f32 v114, v122, v123
	v_cvt_pk_bf16_f32 v115, v120, v121
	v_mul_f32_e32 v126, v123, v123
	v_fmac_f32_e32 v124, v116, v116
	v_fmac_f32_e32 v125, v118, v118
	v_mul_f32_e32 v127, v121, v121
	global_store_dwordx4 v[196:197], v[112:115], off offset:256
	v_fmac_f32_e32 v126, v122, v122
	v_fmac_f32_e32 v127, v120, v120
	v_add_f32_e32 v112, v124, v125
	v_add_f32_e32 v112, v112, v126
	v_add_f32_e32 v112, v127, v112
	v_add_f32_e32 v115, v130, v112
	v_mov_b32_e32 v124, v115
	s_nop 1
	v_permlane16_swap_b32_e32 v124, v115
	v_pk_mul_f32 v[112:113], v[140:141], v[116:117]
	v_pk_mul_f32 v[118:119], v[142:143], v[118:119]
	v_cvt_pk_bf16_f32 v114, v112, v113
	v_pk_mul_f32 v[120:121], v[136:137], v[120:121]
	s_waitcnt lgkmcnt(0)
	v_add_f32_e32 v112, v115, v124
	v_mov_b32_e32 v113, v112
	s_nop 1
	v_permlane32_swap_b32_e32 v113, v112
	v_pk_mul_f32 v[116:117], v[138:139], v[122:123]
	v_cvt_pk_bf16_f32 v115, v118, v119
	v_cvt_pk_bf16_f32 v116, v116, v117
	v_cvt_pk_bf16_f32 v117, v120, v121
	global_store_dwordx4 v[194:195], v[114:117], off offset:256
	s_and_saveexec_b64 s[24:25], s[2:3]
	s_cbranch_execz .LBB0_1016
	v_lshl_add_u64 v[114:115], v[128:129], 2, s[14:15]
	s_waitcnt lgkmcnt(0)
	v_add_f32_e32 v112, v112, v113
	global_atomic_add_f32 v[114:115], v112, off
.LBB0_1016:
	s_or_b64 exec, exec, s[24:25]
	v_add_u32_e32 v112, s17, v179
	s_waitcnt lgkmcnt(0)
	v_ashrrev_i32_e32 v113, 31, v112
	v_lshlrev_b64 v[114:115], 12, v[112:113]
	v_lshl_add_u64 v[114:115], s[64:65], 0, v[114:115]
	v_lshl_add_u64 v[122:123], v[162:163], 2, v[114:115]
	global_load_dwordx4 v[114:117], v[122:123], off
	global_load_dwordx4 v[118:121], v[122:123], off offset:16
	v_lshlrev_b64 v[124:125], 11, v[112:113]
	v_lshl_add_u64 v[126:127], s[52:53], 0, v[124:125]
	v_lshl_add_u64 v[124:125], s[12:13], 0, v[124:125]
	v_lshl_add_u64 v[126:127], v[126:127], 0, v[164:165]
	v_lshl_add_u64 v[124:125], v[124:125], 0, v[164:165]
	s_waitcnt vmcnt(1)
	v_pk_fma_f32 v[116:117], v[110:111], v[90:91], v[116:117]
	v_pk_fma_f32 v[114:115], v[108:109], v[88:89], v[114:115]
	s_waitcnt vmcnt(0)
	v_pk_fma_f32 v[120:121], v[106:107], v[86:87], v[120:121]
	v_pk_fma_f32 v[118:119], v[104:105], v[84:85], v[118:119]
	v_cvt_pk_bf16_f32 v104, v114, v115
	v_cvt_pk_bf16_f32 v105, v116, v117
	v_cvt_pk_bf16_f32 v106, v118, v119
	v_cvt_pk_bf16_f32 v107, v120, v121
	v_pk_mul_f32 v[108:109], v[170:171], v[116:117]
	v_pk_mul_f32 v[110:111], v[174:175], v[114:115]
	v_pk_mul_f32 v[128:129], v[168:169], v[120:121]
	v_pk_mul_f32 v[130:131], v[172:173], v[118:119]
	global_store_dwordx4 v[126:127], v[104:107], off
	v_mul_f32_e32 v115, v115, v115
	v_mul_f32_e32 v117, v117, v117
	v_cvt_pk_bf16_f32 v104, v110, v111
	v_cvt_pk_bf16_f32 v105, v108, v109
	v_cvt_pk_bf16_f32 v106, v130, v131
	v_cvt_pk_bf16_f32 v107, v128, v129
	global_store_dwordx4 v[124:125], v[104:107], off
	global_load_dwordx4 v[104:107], v[122:123], off offset:512
	s_nop 0
	global_load_dwordx4 v[108:111], v[122:123], off offset:528
	v_mul_f32_e32 v119, v119, v119
	v_fmac_f32_e32 v115, v114, v114
	v_fmac_f32_e32 v117, v116, v116
	v_mul_f32_e32 v121, v121, v121
	v_fmac_f32_e32 v119, v118, v118
	v_add_f32_e32 v114, v115, v117
	v_fmac_f32_e32 v121, v120, v120
	v_add_f32_e32 v114, v114, v119
	v_add_f32_e32 v114, v121, v114
	s_waitcnt vmcnt(1)
	v_pk_fma_f32 v[102:103], v[102:103], v[94:95], v[106:107]
	v_pk_fma_f32 v[100:101], v[100:101], v[92:93], v[104:105]
	s_waitcnt vmcnt(0)
	v_pk_fma_f32 v[104:105], v[98:99], v[82:83], v[110:111]
	v_pk_fma_f32 v[106:107], v[96:97], v[80:81], v[108:109]
	v_mul_f32_e32 v108, v101, v101
	v_mul_f32_e32 v109, v103, v103
	v_cvt_pk_bf16_f32 v96, v100, v101
	v_cvt_pk_bf16_f32 v97, v102, v103
	v_cvt_pk_bf16_f32 v98, v106, v107
	v_cvt_pk_bf16_f32 v99, v104, v105
	v_mul_f32_e32 v110, v107, v107
	v_fmac_f32_e32 v108, v100, v100
	v_fmac_f32_e32 v109, v102, v102
	v_mul_f32_e32 v111, v105, v105
	global_store_dwordx4 v[126:127], v[96:99], off offset:256
	v_fmac_f32_e32 v110, v106, v106
	v_fmac_f32_e32 v111, v104, v104
	v_add_f32_e32 v96, v108, v109
	v_add_f32_e32 v96, v96, v110
	v_add_f32_e32 v96, v111, v96
	v_add_f32_e32 v99, v114, v96
	v_mov_b32_e32 v108, v99
	s_nop 1
	v_permlane16_swap_b32_e32 v108, v99
	v_pk_mul_f32 v[96:97], v[140:141], v[100:101]
	v_pk_mul_f32 v[102:103], v[142:143], v[102:103]
	v_cvt_pk_bf16_f32 v98, v96, v97
	v_pk_mul_f32 v[104:105], v[136:137], v[104:105]
	s_waitcnt lgkmcnt(0)
	v_add_f32_e32 v96, v99, v108
	v_mov_b32_e32 v97, v96
	s_nop 1
	v_permlane32_swap_b32_e32 v97, v96
	v_pk_mul_f32 v[100:101], v[138:139], v[106:107]
	v_cvt_pk_bf16_f32 v99, v102, v103
	v_cvt_pk_bf16_f32 v100, v100, v101
	v_cvt_pk_bf16_f32 v101, v104, v105
	global_store_dwordx4 v[124:125], v[98:101], off offset:256
	s_and_saveexec_b64 s[24:25], s[2:3]
	s_cbranch_execz .LBB0_1018
	v_lshl_add_u64 v[98:99], v[112:113], 2, s[14:15]
	s_waitcnt lgkmcnt(0)
	v_add_f32_e32 v96, v96, v97
	global_atomic_add_f32 v[98:99], v96, off
.LBB0_1018:
	s_or_b64 exec, exec, s[24:25]
	v_add_u32_e32 v96, s17, v180
	s_waitcnt lgkmcnt(0)
	v_ashrrev_i32_e32 v97, 31, v96
	v_lshlrev_b64 v[98:99], 12, v[96:97]
	v_lshl_add_u64 v[98:99], s[64:65], 0, v[98:99]
	v_lshl_add_u64 v[106:107], v[162:163], 2, v[98:99]
	global_load_dwordx4 v[98:101], v[106:107], off
	global_load_dwordx4 v[102:105], v[106:107], off offset:16
	v_lshlrev_b64 v[108:109], 11, v[96:97]
	v_lshl_add_u64 v[110:111], s[52:53], 0, v[108:109]
	v_lshl_add_u64 v[108:109], s[12:13], 0, v[108:109]
	v_lshl_add_u64 v[110:111], v[110:111], 0, v[164:165]
	v_lshl_add_u64 v[108:109], v[108:109], 0, v[164:165]
	s_waitcnt vmcnt(1)
	v_pk_fma_f32 v[100:101], v[78:79], v[90:91], v[100:101]
	v_pk_fma_f32 v[98:99], v[76:77], v[88:89], v[98:99]
	s_waitcnt vmcnt(0)
	v_pk_fma_f32 v[104:105], v[74:75], v[86:87], v[104:105]
	v_pk_fma_f32 v[102:103], v[72:73], v[84:85], v[102:103]
	v_cvt_pk_bf16_f32 v72, v98, v99
	v_cvt_pk_bf16_f32 v73, v100, v101
	v_cvt_pk_bf16_f32 v74, v102, v103
	v_cvt_pk_bf16_f32 v75, v104, v105
	v_pk_mul_f32 v[76:77], v[170:171], v[100:101]
	v_pk_mul_f32 v[78:79], v[174:175], v[98:99]
	v_pk_mul_f32 v[112:113], v[168:169], v[104:105]
	v_pk_mul_f32 v[114:115], v[172:173], v[102:103]
	global_store_dwordx4 v[110:111], v[72:75], off
	v_mul_f32_e32 v99, v99, v99
	v_mul_f32_e32 v101, v101, v101
	v_cvt_pk_bf16_f32 v72, v78, v79
	v_cvt_pk_bf16_f32 v73, v76, v77
	v_cvt_pk_bf16_f32 v74, v114, v115
	v_cvt_pk_bf16_f32 v75, v112, v113
	global_store_dwordx4 v[108:109], v[72:75], off
	global_load_dwordx4 v[72:75], v[106:107], off offset:512
	s_nop 0
	global_load_dwordx4 v[76:79], v[106:107], off offset:528
	v_mul_f32_e32 v103, v103, v103
	v_fmac_f32_e32 v99, v98, v98
	v_fmac_f32_e32 v101, v100, v100
	v_mul_f32_e32 v105, v105, v105
	v_fmac_f32_e32 v103, v102, v102
	v_add_f32_e32 v98, v99, v101
	v_fmac_f32_e32 v105, v104, v104
	v_add_f32_e32 v98, v98, v103
	v_add_f32_e32 v98, v105, v98
	s_waitcnt vmcnt(1)
	v_pk_fma_f32 v[70:71], v[70:71], v[94:95], v[74:75]
	v_pk_fma_f32 v[68:69], v[68:69], v[92:93], v[72:73]
	s_waitcnt vmcnt(0)
	v_pk_fma_f32 v[72:73], v[66:67], v[82:83], v[78:79]
	v_pk_fma_f32 v[74:75], v[64:65], v[80:81], v[76:77]
	v_mul_f32_e32 v76, v69, v69
	v_mul_f32_e32 v77, v71, v71
	v_cvt_pk_bf16_f32 v64, v68, v69
	v_cvt_pk_bf16_f32 v65, v70, v71
	v_cvt_pk_bf16_f32 v66, v74, v75
	v_cvt_pk_bf16_f32 v67, v72, v73
	v_mul_f32_e32 v78, v75, v75
	v_fmac_f32_e32 v76, v68, v68
	v_fmac_f32_e32 v77, v70, v70
	v_mul_f32_e32 v79, v73, v73
	global_store_dwordx4 v[110:111], v[64:67], off offset:256
	v_fmac_f32_e32 v78, v74, v74
	v_fmac_f32_e32 v79, v72, v72
	v_add_f32_e32 v64, v76, v77
	v_add_f32_e32 v64, v64, v78
	v_add_f32_e32 v64, v79, v64
	v_add_f32_e32 v67, v98, v64
	v_mov_b32_e32 v76, v67
	s_nop 1
	v_permlane16_swap_b32_e32 v76, v67
	v_pk_mul_f32 v[64:65], v[140:141], v[68:69]
	v_pk_mul_f32 v[70:71], v[142:143], v[70:71]
	v_cvt_pk_bf16_f32 v66, v64, v65
	v_pk_mul_f32 v[72:73], v[136:137], v[72:73]
	s_waitcnt lgkmcnt(0)
	v_add_f32_e32 v64, v67, v76
	v_mov_b32_e32 v65, v64
	s_nop 1
	v_permlane32_swap_b32_e32 v65, v64
	v_pk_mul_f32 v[68:69], v[138:139], v[74:75]
	v_cvt_pk_bf16_f32 v67, v70, v71
	v_cvt_pk_bf16_f32 v68, v68, v69
	v_cvt_pk_bf16_f32 v69, v72, v73
	global_store_dwordx4 v[108:109], v[66:69], off offset:256
	s_and_saveexec_b64 s[24:25], s[2:3]
	s_cbranch_execz .LBB0_1020
	v_lshl_add_u64 v[66:67], v[96:97], 2, s[14:15]
	s_waitcnt lgkmcnt(0)
	v_add_f32_e32 v64, v64, v65
	global_atomic_add_f32 v[66:67], v64, off
.LBB0_1020:
	s_or_b64 exec, exec, s[24:25]
	v_add_u32_e32 v64, 0x80, v166
	s_waitcnt lgkmcnt(0)
	v_ashrrev_i32_e32 v65, 31, v64
	v_lshlrev_b64 v[66:67], 12, v[64:65]
	v_lshl_add_u64 v[66:67], s[64:65], 0, v[66:67]
	v_lshl_add_u64 v[74:75], v[162:163], 2, v[66:67]
	global_load_dwordx4 v[66:69], v[74:75], off
	global_load_dwordx4 v[70:73], v[74:75], off offset:16
	v_lshlrev_b64 v[76:77], 11, v[64:65]
	v_lshl_add_u64 v[78:79], s[52:53], 0, v[76:77]
	v_lshl_add_u64 v[76:77], s[12:13], 0, v[76:77]
	v_lshl_add_u64 v[78:79], v[78:79], 0, v[164:165]
	v_lshl_add_u64 v[76:77], v[76:77], 0, v[164:165]
	s_waitcnt vmcnt(1)
	v_pk_fma_f32 v[68:69], v[62:63], v[90:91], v[68:69]
	v_pk_fma_f32 v[66:67], v[60:61], v[88:89], v[66:67]
	s_waitcnt vmcnt(0)
	v_pk_fma_f32 v[72:73], v[58:59], v[86:87], v[72:73]
	v_pk_fma_f32 v[70:71], v[56:57], v[84:85], v[70:71]
	v_cvt_pk_bf16_f32 v56, v66, v67
	v_cvt_pk_bf16_f32 v57, v68, v69
	v_cvt_pk_bf16_f32 v58, v70, v71
	v_cvt_pk_bf16_f32 v59, v72, v73
	v_pk_mul_f32 v[60:61], v[170:171], v[68:69]
	v_pk_mul_f32 v[62:63], v[174:175], v[66:67]
	v_pk_mul_f32 v[96:97], v[168:169], v[72:73]
	v_pk_mul_f32 v[98:99], v[172:173], v[70:71]
	global_store_dwordx4 v[78:79], v[56:59], off
	v_mul_f32_e32 v67, v67, v67
	v_mul_f32_e32 v69, v69, v69
	v_cvt_pk_bf16_f32 v56, v62, v63
	v_cvt_pk_bf16_f32 v57, v60, v61
	v_cvt_pk_bf16_f32 v58, v98, v99
	v_cvt_pk_bf16_f32 v59, v96, v97
	global_store_dwordx4 v[76:77], v[56:59], off
	global_load_dwordx4 v[56:59], v[74:75], off offset:512
	s_nop 0
	global_load_dwordx4 v[60:63], v[74:75], off offset:528
	v_mul_f32_e32 v71, v71, v71
	v_fmac_f32_e32 v67, v66, v66
	v_fmac_f32_e32 v69, v68, v68
	v_mul_f32_e32 v73, v73, v73
	v_fmac_f32_e32 v71, v70, v70
	v_add_f32_e32 v66, v67, v69
	v_fmac_f32_e32 v73, v72, v72
	v_add_f32_e32 v66, v66, v71
	v_add_f32_e32 v66, v73, v66
	s_waitcnt vmcnt(1)
	v_pk_fma_f32 v[54:55], v[54:55], v[94:95], v[58:59]
	v_pk_fma_f32 v[52:53], v[52:53], v[92:93], v[56:57]
	s_waitcnt vmcnt(0)
	v_pk_fma_f32 v[56:57], v[50:51], v[82:83], v[62:63]
	v_pk_fma_f32 v[58:59], v[48:49], v[80:81], v[60:61]
	v_mul_f32_e32 v60, v53, v53
	v_mul_f32_e32 v61, v55, v55
	v_cvt_pk_bf16_f32 v48, v52, v53
	v_cvt_pk_bf16_f32 v49, v54, v55
	v_cvt_pk_bf16_f32 v50, v58, v59
	v_cvt_pk_bf16_f32 v51, v56, v57
	v_mul_f32_e32 v62, v59, v59
	v_fmac_f32_e32 v60, v52, v52
	v_fmac_f32_e32 v61, v54, v54
	v_mul_f32_e32 v63, v57, v57
	global_store_dwordx4 v[78:79], v[48:51], off offset:256
	v_fmac_f32_e32 v62, v58, v58
	v_fmac_f32_e32 v63, v56, v56
	v_add_f32_e32 v48, v60, v61
	v_add_f32_e32 v48, v48, v62
	v_add_f32_e32 v48, v63, v48
	v_add_f32_e32 v51, v66, v48
	v_mov_b32_e32 v60, v51
	s_nop 1
	v_permlane16_swap_b32_e32 v60, v51
	v_pk_mul_f32 v[48:49], v[140:141], v[52:53]
	v_pk_mul_f32 v[54:55], v[142:143], v[54:55]
	v_cvt_pk_bf16_f32 v50, v48, v49
	v_pk_mul_f32 v[56:57], v[136:137], v[56:57]
	s_waitcnt lgkmcnt(0)
	v_add_f32_e32 v48, v51, v60
	v_mov_b32_e32 v49, v48
	s_nop 1
	v_permlane32_swap_b32_e32 v49, v48
	v_pk_mul_f32 v[52:53], v[138:139], v[58:59]
	v_cvt_pk_bf16_f32 v51, v54, v55
	v_cvt_pk_bf16_f32 v52, v52, v53
	v_cvt_pk_bf16_f32 v53, v56, v57
	global_store_dwordx4 v[76:77], v[50:53], off offset:256
	s_and_saveexec_b64 s[24:25], s[2:3]
	s_cbranch_execz .LBB0_1022
	v_lshl_add_u64 v[50:51], v[64:65], 2, s[14:15]
	s_waitcnt lgkmcnt(0)
	v_add_f32_e32 v48, v48, v49
	global_atomic_add_f32 v[50:51], v48, off
.LBB0_1022:
	s_or_b64 exec, exec, s[24:25]
	v_add_u32_e32 v48, 0x90, v166
	s_waitcnt lgkmcnt(0)
	v_ashrrev_i32_e32 v49, 31, v48
	v_lshlrev_b64 v[50:51], 12, v[48:49]
	v_lshl_add_u64 v[50:51], s[64:65], 0, v[50:51]
	v_lshl_add_u64 v[58:59], v[162:163], 2, v[50:51]
	global_load_dwordx4 v[50:53], v[58:59], off
	global_load_dwordx4 v[54:57], v[58:59], off offset:16
	v_lshlrev_b64 v[60:61], 11, v[48:49]
	v_lshl_add_u64 v[62:63], s[52:53], 0, v[60:61]
	v_lshl_add_u64 v[60:61], s[12:13], 0, v[60:61]
	v_lshl_add_u64 v[62:63], v[62:63], 0, v[164:165]
	v_lshl_add_u64 v[60:61], v[60:61], 0, v[164:165]
	s_waitcnt vmcnt(1)
	v_pk_fma_f32 v[52:53], v[46:47], v[90:91], v[52:53]
	v_pk_fma_f32 v[50:51], v[44:45], v[88:89], v[50:51]
	s_waitcnt vmcnt(0)
	v_pk_fma_f32 v[56:57], v[42:43], v[86:87], v[56:57]
	v_pk_fma_f32 v[54:55], v[40:41], v[84:85], v[54:55]
	v_cvt_pk_bf16_f32 v40, v50, v51
	v_cvt_pk_bf16_f32 v41, v52, v53
	v_cvt_pk_bf16_f32 v42, v54, v55
	v_cvt_pk_bf16_f32 v43, v56, v57
	v_pk_mul_f32 v[44:45], v[170:171], v[52:53]
	v_pk_mul_f32 v[46:47], v[174:175], v[50:51]
	v_pk_mul_f32 v[64:65], v[168:169], v[56:57]
	v_pk_mul_f32 v[66:67], v[172:173], v[54:55]
	global_store_dwordx4 v[62:63], v[40:43], off
	v_mul_f32_e32 v51, v51, v51
	v_mul_f32_e32 v53, v53, v53
	v_cvt_pk_bf16_f32 v40, v46, v47
	v_cvt_pk_bf16_f32 v41, v44, v45
	v_cvt_pk_bf16_f32 v42, v66, v67
	v_cvt_pk_bf16_f32 v43, v64, v65
	global_store_dwordx4 v[60:61], v[40:43], off
	global_load_dwordx4 v[40:43], v[58:59], off offset:512
	s_nop 0
	global_load_dwordx4 v[44:47], v[58:59], off offset:528
	v_mul_f32_e32 v55, v55, v55
	v_fmac_f32_e32 v51, v50, v50
	v_fmac_f32_e32 v53, v52, v52
	v_mul_f32_e32 v57, v57, v57
	v_fmac_f32_e32 v55, v54, v54
	v_add_f32_e32 v50, v51, v53
	v_fmac_f32_e32 v57, v56, v56
	v_add_f32_e32 v50, v50, v55
	v_add_f32_e32 v50, v57, v50
	s_waitcnt vmcnt(1)
	v_pk_fma_f32 v[38:39], v[38:39], v[94:95], v[42:43]
	v_pk_fma_f32 v[36:37], v[36:37], v[92:93], v[40:41]
	s_waitcnt vmcnt(0)
	v_pk_fma_f32 v[40:41], v[34:35], v[82:83], v[46:47]
	v_pk_fma_f32 v[42:43], v[32:33], v[80:81], v[44:45]
	v_mul_f32_e32 v44, v37, v37
	v_mul_f32_e32 v45, v39, v39
	v_cvt_pk_bf16_f32 v32, v36, v37
	v_cvt_pk_bf16_f32 v33, v38, v39
	v_cvt_pk_bf16_f32 v34, v42, v43
	v_cvt_pk_bf16_f32 v35, v40, v41
	v_mul_f32_e32 v46, v43, v43
	v_fmac_f32_e32 v44, v36, v36
	v_fmac_f32_e32 v45, v38, v38
	v_mul_f32_e32 v47, v41, v41
	global_store_dwordx4 v[62:63], v[32:35], off offset:256
	v_fmac_f32_e32 v46, v42, v42
	v_fmac_f32_e32 v47, v40, v40
	v_add_f32_e32 v32, v44, v45
	v_add_f32_e32 v32, v32, v46
	v_add_f32_e32 v32, v47, v32
	v_add_f32_e32 v35, v50, v32
	v_mov_b32_e32 v44, v35
	s_nop 1
	v_permlane16_swap_b32_e32 v44, v35
	v_pk_mul_f32 v[32:33], v[140:141], v[36:37]
	v_pk_mul_f32 v[38:39], v[142:143], v[38:39]
	v_cvt_pk_bf16_f32 v34, v32, v33
	v_pk_mul_f32 v[40:41], v[136:137], v[40:41]
	s_waitcnt lgkmcnt(0)
	v_add_f32_e32 v32, v35, v44
	v_mov_b32_e32 v33, v32
	s_nop 1
	v_permlane32_swap_b32_e32 v33, v32
	v_pk_mul_f32 v[36:37], v[138:139], v[42:43]
	v_cvt_pk_bf16_f32 v35, v38, v39
	v_cvt_pk_bf16_f32 v36, v36, v37
	v_cvt_pk_bf16_f32 v37, v40, v41
	global_store_dwordx4 v[60:61], v[34:37], off offset:256
	s_and_saveexec_b64 s[24:25], s[2:3]
	s_cbranch_execz .LBB0_1024
	v_lshl_add_u64 v[34:35], v[48:49], 2, s[14:15]
	s_waitcnt lgkmcnt(0)
	v_add_f32_e32 v32, v32, v33
	global_atomic_add_f32 v[34:35], v32, off
.LBB0_1024:
	s_or_b64 exec, exec, s[24:25]
	v_add_u32_e32 v32, 0xa0, v166
	s_waitcnt lgkmcnt(0)
	v_ashrrev_i32_e32 v33, 31, v32
	v_lshlrev_b64 v[34:35], 12, v[32:33]
	v_lshl_add_u64 v[34:35], s[64:65], 0, v[34:35]
	v_lshl_add_u64 v[42:43], v[162:163], 2, v[34:35]
	global_load_dwordx4 v[34:37], v[42:43], off
	global_load_dwordx4 v[38:41], v[42:43], off offset:16
	v_lshlrev_b64 v[44:45], 11, v[32:33]
	v_lshl_add_u64 v[46:47], s[52:53], 0, v[44:45]
	v_lshl_add_u64 v[44:45], s[12:13], 0, v[44:45]
	v_lshl_add_u64 v[46:47], v[46:47], 0, v[164:165]
	v_lshl_add_u64 v[44:45], v[44:45], 0, v[164:165]
	s_waitcnt vmcnt(1)
	v_pk_fma_f32 v[36:37], v[30:31], v[90:91], v[36:37]
	v_pk_fma_f32 v[34:35], v[28:29], v[88:89], v[34:35]
	s_waitcnt vmcnt(0)
	v_pk_fma_f32 v[40:41], v[26:27], v[86:87], v[40:41]
	v_pk_fma_f32 v[38:39], v[24:25], v[84:85], v[38:39]
	v_cvt_pk_bf16_f32 v24, v34, v35
	v_cvt_pk_bf16_f32 v25, v36, v37
	v_cvt_pk_bf16_f32 v26, v38, v39
	v_cvt_pk_bf16_f32 v27, v40, v41
	v_pk_mul_f32 v[28:29], v[170:171], v[36:37]
	v_pk_mul_f32 v[30:31], v[174:175], v[34:35]
	v_pk_mul_f32 v[48:49], v[168:169], v[40:41]
	v_pk_mul_f32 v[50:51], v[172:173], v[38:39]
	global_store_dwordx4 v[46:47], v[24:27], off
	v_mul_f32_e32 v35, v35, v35
	v_mul_f32_e32 v37, v37, v37
	v_cvt_pk_bf16_f32 v24, v30, v31
	v_cvt_pk_bf16_f32 v25, v28, v29
	v_cvt_pk_bf16_f32 v26, v50, v51
	v_cvt_pk_bf16_f32 v27, v48, v49
	global_store_dwordx4 v[44:45], v[24:27], off
	global_load_dwordx4 v[24:27], v[42:43], off offset:512
	s_nop 0
	global_load_dwordx4 v[28:31], v[42:43], off offset:528
	v_mul_f32_e32 v39, v39, v39
	v_fmac_f32_e32 v35, v34, v34
	v_fmac_f32_e32 v37, v36, v36
	v_mul_f32_e32 v41, v41, v41
	v_fmac_f32_e32 v39, v38, v38
	v_add_f32_e32 v34, v35, v37
	v_fmac_f32_e32 v41, v40, v40
	v_add_f32_e32 v34, v34, v39
	v_add_f32_e32 v34, v41, v34
	s_waitcnt vmcnt(1)
	v_pk_fma_f32 v[22:23], v[22:23], v[94:95], v[26:27]
	v_pk_fma_f32 v[20:21], v[20:21], v[92:93], v[24:25]
	s_waitcnt vmcnt(0)
	v_pk_fma_f32 v[24:25], v[18:19], v[82:83], v[30:31]
	v_pk_fma_f32 v[26:27], v[16:17], v[80:81], v[28:29]
	v_mul_f32_e32 v28, v21, v21
	v_mul_f32_e32 v29, v23, v23
	v_cvt_pk_bf16_f32 v16, v20, v21
	v_cvt_pk_bf16_f32 v17, v22, v23
	v_cvt_pk_bf16_f32 v18, v26, v27
	v_cvt_pk_bf16_f32 v19, v24, v25
	v_mul_f32_e32 v30, v27, v27
	v_fmac_f32_e32 v28, v20, v20
	v_fmac_f32_e32 v29, v22, v22
	v_mul_f32_e32 v31, v25, v25
	global_store_dwordx4 v[46:47], v[16:19], off offset:256
	v_fmac_f32_e32 v30, v26, v26
	v_fmac_f32_e32 v31, v24, v24
	v_add_f32_e32 v16, v28, v29
	v_add_f32_e32 v16, v16, v30
	v_add_f32_e32 v16, v31, v16
	v_add_f32_e32 v19, v34, v16
	v_mov_b32_e32 v28, v19
	s_nop 1
	v_permlane16_swap_b32_e32 v28, v19
	v_pk_mul_f32 v[16:17], v[140:141], v[20:21]
	v_pk_mul_f32 v[22:23], v[142:143], v[22:23]
	v_cvt_pk_bf16_f32 v18, v16, v17
	v_pk_mul_f32 v[24:25], v[136:137], v[24:25]
	s_waitcnt lgkmcnt(0)
	v_add_f32_e32 v16, v19, v28
	v_mov_b32_e32 v17, v16
	s_nop 1
	v_permlane32_swap_b32_e32 v17, v16
	v_pk_mul_f32 v[20:21], v[138:139], v[26:27]
	v_cvt_pk_bf16_f32 v19, v22, v23
	v_cvt_pk_bf16_f32 v20, v20, v21
	v_cvt_pk_bf16_f32 v21, v24, v25
	global_store_dwordx4 v[44:45], v[18:21], off offset:256
	s_and_saveexec_b64 s[24:25], s[2:3]
	s_cbranch_execz .LBB0_1026
	v_lshl_add_u64 v[18:19], v[32:33], 2, s[14:15]
	s_waitcnt lgkmcnt(0)
	v_add_f32_e32 v16, v16, v17
	global_atomic_add_f32 v[18:19], v16, off
.LBB0_1026:
	s_or_b64 exec, exec, s[24:25]
	v_add_u32_e32 v16, 0xb0, v166
	s_waitcnt lgkmcnt(0)
	v_ashrrev_i32_e32 v17, 31, v16
	v_lshlrev_b64 v[18:19], 12, v[16:17]
	v_lshl_add_u64 v[18:19], s[64:65], 0, v[18:19]
	v_lshl_add_u64 v[26:27], v[162:163], 2, v[18:19]
	global_load_dwordx4 v[18:21], v[26:27], off
	global_load_dwordx4 v[22:25], v[26:27], off offset:16
	v_lshlrev_b64 v[28:29], 11, v[16:17]
	v_lshl_add_u64 v[30:31], s[52:53], 0, v[28:29]
	v_lshl_add_u64 v[28:29], s[12:13], 0, v[28:29]
	v_lshl_add_u64 v[30:31], v[30:31], 0, v[164:165]
	v_lshl_add_u64 v[28:29], v[28:29], 0, v[164:165]
	s_waitcnt vmcnt(1)
	v_pk_fma_f32 v[20:21], v[14:15], v[90:91], v[20:21]
	v_pk_fma_f32 v[18:19], v[12:13], v[88:89], v[18:19]
	s_waitcnt vmcnt(0)
	v_pk_fma_f32 v[24:25], v[10:11], v[86:87], v[24:25]
	v_pk_fma_f32 v[22:23], v[8:9], v[84:85], v[22:23]
	v_cvt_pk_bf16_f32 v8, v18, v19
	v_cvt_pk_bf16_f32 v9, v20, v21
	v_cvt_pk_bf16_f32 v10, v22, v23
	v_cvt_pk_bf16_f32 v11, v24, v25
	v_pk_mul_f32 v[12:13], v[170:171], v[20:21]
	v_pk_mul_f32 v[14:15], v[174:175], v[18:19]
	v_pk_mul_f32 v[32:33], v[168:169], v[24:25]
	v_pk_mul_f32 v[34:35], v[172:173], v[22:23]
	global_store_dwordx4 v[30:31], v[8:11], off
	v_mul_f32_e32 v19, v19, v19
	v_mul_f32_e32 v21, v21, v21
	v_cvt_pk_bf16_f32 v8, v14, v15
	v_cvt_pk_bf16_f32 v9, v12, v13
	v_cvt_pk_bf16_f32 v10, v34, v35
	v_cvt_pk_bf16_f32 v11, v32, v33
	global_store_dwordx4 v[28:29], v[8:11], off
	global_load_dwordx4 v[8:11], v[26:27], off offset:512
	s_nop 0
	global_load_dwordx4 v[12:15], v[26:27], off offset:528
	v_mul_f32_e32 v23, v23, v23
	v_fmac_f32_e32 v19, v18, v18
	v_fmac_f32_e32 v21, v20, v20
	v_mul_f32_e32 v25, v25, v25
	v_fmac_f32_e32 v23, v22, v22
	v_add_f32_e32 v18, v19, v21
	v_fmac_f32_e32 v25, v24, v24
	v_add_f32_e32 v18, v18, v23
	v_add_f32_e32 v18, v25, v18
	s_waitcnt vmcnt(1)
	v_pk_fma_f32 v[6:7], v[6:7], v[94:95], v[10:11]
	v_pk_fma_f32 v[4:5], v[4:5], v[92:93], v[8:9]
	s_waitcnt vmcnt(0)
	v_pk_fma_f32 v[8:9], v[2:3], v[82:83], v[14:15]
	v_pk_fma_f32 v[10:11], v[0:1], v[80:81], v[12:13]
	v_mul_f32_e32 v12, v5, v5
	v_mul_f32_e32 v13, v7, v7
	v_cvt_pk_bf16_f32 v0, v4, v5
	v_cvt_pk_bf16_f32 v1, v6, v7
	v_cvt_pk_bf16_f32 v2, v10, v11
	v_cvt_pk_bf16_f32 v3, v8, v9
	v_mul_f32_e32 v14, v11, v11
	v_fmac_f32_e32 v12, v4, v4
	v_fmac_f32_e32 v13, v6, v6
	v_mul_f32_e32 v15, v9, v9
	global_store_dwordx4 v[30:31], v[0:3], off offset:256
	v_fmac_f32_e32 v14, v10, v10
	v_fmac_f32_e32 v15, v8, v8
	v_add_f32_e32 v0, v12, v13
	v_add_f32_e32 v0, v0, v14
	v_add_f32_e32 v0, v15, v0
	v_add_f32_e32 v3, v18, v0
	v_mov_b32_e32 v12, v3
	s_nop 1
	v_permlane16_swap_b32_e32 v12, v3
	v_pk_mul_f32 v[0:1], v[140:141], v[4:5]
	v_pk_mul_f32 v[6:7], v[142:143], v[6:7]
	v_cvt_pk_bf16_f32 v2, v0, v1
	v_pk_mul_f32 v[8:9], v[136:137], v[8:9]
	s_waitcnt lgkmcnt(0)
	v_add_f32_e32 v0, v3, v12
	v_mov_b32_e32 v1, v0
	s_nop 1
	v_permlane32_swap_b32_e32 v1, v0
	v_pk_mul_f32 v[4:5], v[138:139], v[10:11]
	v_cvt_pk_bf16_f32 v3, v6, v7
	v_cvt_pk_bf16_f32 v4, v4, v5
	v_cvt_pk_bf16_f32 v5, v8, v9
	global_store_dwordx4 v[28:29], v[2:5], off offset:256
	s_and_saveexec_b64 s[24:25], s[2:3]
	s_cbranch_execz .LBB0_1028
	v_lshl_add_u64 v[2:3], v[16:17], 2, s[14:15]
	s_waitcnt lgkmcnt(0)
	v_add_f32_e32 v0, v0, v1
	global_atomic_add_f32 v[2:3], v0, off
